# attention work queue: static s_setprio 1 for waves 4..7 while units run (asm guide 7.4), reset to 0 after the queue; on top of the attention packed split
# speedup vs baseline: 1.0035x; 1.0035x over previous
.LBB0_363:
	v_readfirstlane_b32 s2, v196
	s_cmp_ge_u32 s2, 0x100
	s_cbranch_scc0 .Lattn_prio_done
	s_setprio 1

.LBB0_407:
	s_setprio 0
	s_mov_b64 s[0:1], exec
	v_readlane_b32 s2, v251, 8
	v_readlane_b32 s3, v251, 9
	s_and_b64 s[2:3], s[0:1], s[2:3]
	s_mov_b64 exec, s[2:3]
	s_cbranch_execz .LBB0_417
	v_readlane_b32 s2, v252, 57
	v_readlane_b32 s4, v254, 42
	v_readlane_b32 s5, v254, 43
	s_add_u32 s2, s2, s4
	v_readlane_b32 s3, v252, 58
	s_addc_u32 s3, s3, s5
	s_mov_b32 s6, 0x400001
	s_branch .LBB0_410
